# P8: half of the workgroups (bit 3 of block id) start the gated-merge phase ~10us late so their memory-heavy epilogues overlap the other half's K-loops
# speedup vs baseline: 1.0122x; 1.0056x over previous
.LBB0_1462:
	s_or_b64 exec, exec, s[0:1]
	s_add_u32 s8, s64, 0xac40000
	v_mov_b32_e32 v12, v162
	s_waitcnt lgkmcnt(0)
	s_barrier
	s_cselect_b32 s101, 1, 0
	s_bitcmp1_b32 s2, 3
	s_cbranch_scc0 .Lp8_nodelay
	s_sleep 127
	s_sleep 127
.Lp8_nodelay:
	s_cmp_lg_u32 s101, 0
	s_addc_u32 s9, s65, 0
	s_movk_i32 s18, 0x200
	v_readfirstlane_b32 s36, v12
	s_movk_i32 s37, 0x200
	s_movk_i32 s4, 0x200
	s_movk_i32 s0, 0x200
	s_and_b64 vcc, exec, s[94:95]
	s_cbranch_vccnz .LBB0_1491
	s_ashr_i32 s3, s2, 31
	s_lshr_b32 s1, s3, 29
	s_add_i32 s1, s2, s1
	s_and_b32 s5, s1, -8
	s_sub_i32 s5, s2, s5
	s_cmp_gt_i32 s5, -1
	s_cbranch_scc0 .LBB0_1465
	s_lshl_b32 s24, s5, 6
	s_cbranch_execz .LBB0_1466
	s_branch .LBB0_1467
